# loop-edge rotation (7.11): GEMM K-loop counter updates and next-iteration head address setup moved from after the loop-back barrier into the last MFMA segment
# speedup vs baseline: 1.0028x; 1.0028x over previous
; #define PG8_STAGE(bufoff, gbase, voff) do { _Pragma("unroll") for (int _i = 0; _i < 2; ++_i) \
;         __builtin_amdgcn_global_load_lds((const unsigned*)((const char*)(gbase) + (voff)[_i]), (PG8_LAS unsigned*)(lds + (bufoff) + ldsw + _i * 8192), 16, 0, 0); } while (0)
; #define PG8_LDA(dst, b, h) do { _Pragma("unroll") for (int m = 0; m < 4; ++m) _Pragma("unroll") for (int k = 0; k < 2; ++k) dst[m][k] = *(const PG8_LAS bf16x8*)(lds + PG8_SA(b, h) + aoff + m * 2048 + k * 1024); } while (0)
; #define PG8_LDB(dst, b, h) do { _Pragma("unroll") for (int n = 0; n < 2; ++n) _Pragma("unroll") for (int k = 0; k < 2; ++k) dst[n][k] = *(const PG8_LAS bf16x8*)(lds + PG8_SB(b, h) + boff + n * 2048 + k * 1024); } while (0)
; #define PG8_MMA(ai, bj, At, Bt) do { __builtin_amdgcn_s_setprio(1); _Pragma("unroll") for (int m = 0; m < 4; ++m) _Pragma("unroll") for (int n = 0; n < 2; ++n) _Pragma("unroll") for (int k = 0; k < 2; ++k) \
;         acc[ai][bj][m][n] = __builtin_amdgcn_mfma_f32_16x16x32_bf16(Bt[n][k], At[m][k], acc[ai][bj][m][n], 0, 0, 0); __builtin_amdgcn_s_setprio(0); } while (0)
; #define PG8_WAIT_V(n) asm volatile("s_waitcnt vmcnt(" #n ")" ::: "memory")
; #define PG8_WAIT_L(n) asm volatile("s_waitcnt lgkmcnt(" #n ")" ::: "memory")
; #define PG8_BAR __builtin_amdgcn_s_barrier()
; #define PG8_SCHED __builtin_amdgcn_sched_barrier(0)
; template <class Epi, class Sched, bool ALIGN_EPI = false, bool SP2 = false>
; __device__ __forceinline__ void gemm_phase(PG8_LAS unsigned char* lds, const Gemm g, const Sched& S, const Epi& E) {
;     ...
;             PG8_LDB(B0, 0, 0); PG8_LDB(B1, 0, 1); PG8_SCHED; PG8_LDA(At, 0, 0); PG8_STAGE(PG8_SA(1, 1), a1 + hstep, voffA);
;             PG8_WAIT_V(8); PG8_WAIT_L(0); PG8_BAR; PG8_MMA(0, 0, At, B0); PG8_MMA(0, 1, At, B1); PG8_BAR; PG8_SCHED;
;             PG8_LDA(At, 0, 1); PG8_STAGE(PG8_SB(0, 0), b2, voffB); PG8_STAGE(PG8_SB(0, 1), b2 + hstep, voffB); PG8_STAGE(PG8_SA(0, 0), a2, voffA);
;             PG8_WAIT_V(8); PG8_WAIT_L(0); PG8_BAR; PG8_MMA(1, 0, At, B0); PG8_MMA(1, 1, At, B1); PG8_BAR; PG8_SCHED;
.Lmy_rot2:
	s_add_i32 s15, 0, 0x14000
	ds_read_b128 v[146:149], v154
	ds_read_b128 v[150:153], v154 offset:1024
	ds_read_b128 v[162:165], v154 offset:2048
	ds_read_b128 v[166:169], v154 offset:3072
	v_add_u32_e32 v154, s15, v157
	ds_read_b128 v[170:173], v154
	ds_read_b128 v[174:177], v154 offset:1024
	ds_read_b128 v[178:181], v154 offset:2048
	ds_read_b128 v[186:189], v154 offset:3072
	v_lshl_add_u64 v[154:155], s[60:61], 0, v[144:145]
	s_add_i32 m0, s59, 0xc000
	ds_read_b128 v[190:193], v161
	ds_read_b128 v[194:197], v161 offset:1024
	ds_read_b128 v[198:201], v161 offset:2048
	ds_read_b128 v[202:205], v161 offset:3072
	ds_read_b128 v[208:211], v161 offset:4096
	ds_read_b128 v[212:215], v161 offset:5120
	ds_read_b128 v[216:219], v161 offset:6144
	ds_read_b128 v[220:223], v161 offset:7168
	global_load_lds_dwordx4 v[154:155], off
	v_lshl_add_u64 v[154:155], s[60:61], 0, v[140:141]
	s_add_i32 m0, s59, 0xe000
	s_nop 0
	global_load_lds_dwordx4 v[154:155], off
	s_waitcnt vmcnt(8)
	s_waitcnt lgkmcnt(0)
	s_barrier
	s_setprio 1
	s_waitcnt lgkmcnt(0)
	v_mfma_f32_16x16x32_bf16 v[130:133], v[146:149], v[190:193], v[130:133]
	v_mfma_f32_16x16x32_bf16 v[126:129], v[162:165], v[190:193], v[126:129]
	v_mfma_f32_16x16x32_bf16 v[114:117], v[146:149], v[198:201], v[114:117]
	v_mfma_f32_16x16x32_bf16 v[110:113], v[162:165], v[198:201], v[110:113]
	v_mfma_f32_16x16x32_bf16 v[94:97], v[146:149], v[208:211], v[94:97]
	v_mfma_f32_16x16x32_bf16 v[90:93], v[162:165], v[208:211], v[90:93]
	v_mfma_f32_16x16x32_bf16 v[78:81], v[146:149], v[216:219], v[78:81]
	v_mfma_f32_16x16x32_bf16 v[74:77], v[162:165], v[216:219], v[74:77]
	v_mfma_f32_16x16x32_bf16 v[130:133], v[150:153], v[194:197], v[130:133]
	v_mfma_f32_16x16x32_bf16 v[126:129], v[166:169], v[194:197], v[126:129]
	v_mfma_f32_16x16x32_bf16 v[114:117], v[150:153], v[202:205], v[114:117]
	v_mfma_f32_16x16x32_bf16 v[110:113], v[166:169], v[202:205], v[110:113]
	v_mfma_f32_16x16x32_bf16 v[94:97], v[150:153], v[212:215], v[94:97]
	v_mfma_f32_16x16x32_bf16 v[90:93], v[166:169], v[212:215], v[90:93]
	v_mfma_f32_16x16x32_bf16 v[78:81], v[150:153], v[220:223], v[78:81]
	v_mfma_f32_16x16x32_bf16 v[74:77], v[166:169], v[220:223], v[74:77]
	s_setprio 0
	s_setprio 1
	v_mfma_f32_16x16x32_bf16 v[122:125], v[170:173], v[190:193], v[122:125]
	v_mfma_f32_16x16x32_bf16 v[118:121], v[178:181], v[190:193], v[118:121]
	v_mfma_f32_16x16x32_bf16 v[106:109], v[170:173], v[198:201], v[106:109]
	v_mfma_f32_16x16x32_bf16 v[102:105], v[178:181], v[198:201], v[102:105]
	v_mfma_f32_16x16x32_bf16 v[86:89], v[170:173], v[208:211], v[86:89]
	v_mfma_f32_16x16x32_bf16 v[82:85], v[178:181], v[208:211], v[82:85]
	v_mfma_f32_16x16x32_bf16 v[70:73], v[170:173], v[216:219], v[70:73]
	v_mfma_f32_16x16x32_bf16 v[66:69], v[178:181], v[216:219], v[66:69]
	v_mfma_f32_16x16x32_bf16 v[122:125], v[174:177], v[194:197], v[122:125]
	v_mfma_f32_16x16x32_bf16 v[118:121], v[186:189], v[194:197], v[118:121]
	v_mfma_f32_16x16x32_bf16 v[106:109], v[174:177], v[202:205], v[106:109]
	v_mfma_f32_16x16x32_bf16 v[102:105], v[186:189], v[202:205], v[102:105]
	v_mfma_f32_16x16x32_bf16 v[86:89], v[174:177], v[212:215], v[86:89]
	v_mfma_f32_16x16x32_bf16 v[82:85], v[186:189], v[212:215], v[82:85]
	v_mfma_f32_16x16x32_bf16 v[70:73], v[174:177], v[220:223], v[70:73]
	v_mfma_f32_16x16x32_bf16 v[66:69], v[186:189], v[220:223], v[66:69]
	s_setprio 0
	s_barrier
	s_add_i32 s18, s25, s67
	v_lshl_add_u64 v[154:155], s[62:63], 0, v[0:1]
	s_mov_b32 m0, s18
	ds_read_b128 v[190:193], v161 offset:16384
	ds_read_b128 v[194:197], v161 offset:17408
	ds_read_b128 v[198:201], v161 offset:18432
	ds_read_b128 v[202:205], v161 offset:19456
	ds_read_b128 v[208:211], v161 offset:20480
	ds_read_b128 v[212:215], v161 offset:21504
	ds_read_b128 v[216:219], v161 offset:22528
	ds_read_b128 v[220:223], v161 offset:23552
	global_load_lds_dwordx4 v[154:155], off
	s_add_i32 m0, s18, 0x2000
	s_add_u32 s18, s62, 0x80000
	v_lshl_add_u64 v[182:183], s[62:63], 0, v[138:139]
	s_addc_u32 s19, s63, 0
	s_add_i32 s15, s15, s67
	global_load_lds_dwordx4 v[182:183], off
	v_lshl_add_u64 v[224:225], s[18:19], 0, v[0:1]
	s_mov_b32 m0, s15
	v_lshl_add_u64 v[226:227], s[64:65], 0, v[136:137]
	global_load_lds_dwordx4 v[224:225], off
	v_lshl_add_u64 v[224:225], s[18:19], 0, v[138:139]
	s_add_i32 m0, s15, 0x2000
	s_nop 0
	global_load_lds_dwordx4 v[224:225], off
	v_lshl_add_u64 v[224:225], s[64:65], 0, v[134:135]
	s_mov_b32 m0, s59
	s_nop 0
	global_load_lds_dwordx4 v[224:225], off
	s_mov_b32 m0, s68
	s_nop 0
	global_load_lds_dwordx4 v[226:227], off
	s_waitcnt vmcnt(8)
	s_waitcnt lgkmcnt(0)
	s_barrier
; #define PG8_STAGE(bufoff, gbase, voff) do { _Pragma("unroll") for (int _i = 0; _i < 2; ++_i) \
;         __builtin_amdgcn_global_load_lds((const unsigned*)((const char*)(gbase) + (voff)[_i]), (PG8_LAS unsigned*)(lds + (bufoff) + ldsw + _i * 8192), 16, 0, 0); } while (0)
; #define PG8_LDA(dst, b, h) do { _Pragma("unroll") for (int m = 0; m < 4; ++m) _Pragma("unroll") for (int k = 0; k < 2; ++k) dst[m][k] = *(const PG8_LAS bf16x8*)(lds + PG8_SA(b, h) + aoff + m * 2048 + k * 1024); } while (0)
; #define PG8_LDB(dst, b, h) do { _Pragma("unroll") for (int n = 0; n < 2; ++n) _Pragma("unroll") for (int k = 0; k < 2; ++k) dst[n][k] = *(const PG8_LAS bf16x8*)(lds + PG8_SB(b, h) + boff + n * 2048 + k * 1024); } while (0)
; #define PG8_MMA(ai, bj, At, Bt) do { __builtin_amdgcn_s_setprio(1); _Pragma("unroll") for (int m = 0; m < 4; ++m) _Pragma("unroll") for (int n = 0; n < 2; ++n) _Pragma("unroll") for (int k = 0; k < 2; ++k) \
;         acc[ai][bj][m][n] = __builtin_amdgcn_mfma_f32_16x16x32_bf16(Bt[n][k], At[m][k], acc[ai][bj][m][n], 0, 0, 0); __builtin_amdgcn_s_setprio(0); } while (0)
; #define PG8_WAIT_V(n) asm volatile("s_waitcnt vmcnt(" #n ")" ::: "memory")
; #define PG8_WAIT_L(n) asm volatile("s_waitcnt lgkmcnt(" #n ")" ::: "memory")
; #define PG8_BAR __builtin_amdgcn_s_barrier()
; #define PG8_SCHED __builtin_amdgcn_sched_barrier(0)
; template <class Epi, class Sched, bool ALIGN_EPI = false, bool SP2 = false>
; __device__ __forceinline__ void gemm_phase(PG8_LAS unsigned char* lds, const Gemm g, const Sched& S, const Epi& E) {
;     ...
;             PG8_WAIT_V(8); PG8_WAIT_L(0); PG8_BAR; PG8_MMA(1, 0, At, B0); PG8_MMA(1, 1, At, B1); PG8_BAR; PG8_SCHED;
;             PG8_LDB(B0, 1, 0); PG8_LDB(B1, 1, 1); PG8_SCHED; PG8_LDA(At, 1, 0); PG8_STAGE(PG8_SA(0, 1), a2 + hstep, voffA);
;             PG8_WAIT_V(8); PG8_WAIT_L(0); PG8_BAR; PG8_MMA(0, 0, At, B0); PG8_MMA(0, 1, At, B1); PG8_BAR; PG8_SCHED;
	s_setprio 1
	s_waitcnt lgkmcnt(0)
	v_mfma_f32_16x16x32_bf16 v[62:65], v[146:149], v[190:193], v[62:65]
	v_mfma_f32_16x16x32_bf16 v[58:61], v[162:165], v[190:193], v[58:61]
	v_mfma_f32_16x16x32_bf16 v[46:49], v[146:149], v[198:201], v[46:49]
	v_mfma_f32_16x16x32_bf16 v[42:45], v[162:165], v[198:201], v[42:45]
	v_mfma_f32_16x16x32_bf16 v[30:33], v[146:149], v[208:211], v[30:33]
	v_mfma_f32_16x16x32_bf16 v[26:29], v[162:165], v[208:211], v[26:29]
	v_mfma_f32_16x16x32_bf16 v[14:17], v[146:149], v[216:219], v[14:17]
	v_mfma_f32_16x16x32_bf16 v[10:13], v[162:165], v[216:219], v[10:13]
	v_mfma_f32_16x16x32_bf16 v[62:65], v[150:153], v[194:197], v[62:65]
	v_mfma_f32_16x16x32_bf16 v[58:61], v[166:169], v[194:197], v[58:61]
	v_mfma_f32_16x16x32_bf16 v[46:49], v[150:153], v[202:205], v[46:49]
	v_mfma_f32_16x16x32_bf16 v[42:45], v[166:169], v[202:205], v[42:45]
	v_mfma_f32_16x16x32_bf16 v[30:33], v[150:153], v[212:215], v[30:33]
	v_mfma_f32_16x16x32_bf16 v[26:29], v[166:169], v[212:215], v[26:29]
	v_mfma_f32_16x16x32_bf16 v[14:17], v[150:153], v[220:223], v[14:17]
	v_mfma_f32_16x16x32_bf16 v[10:13], v[166:169], v[220:223], v[10:13]
	s_setprio 0
	s_setprio 1
	v_mfma_f32_16x16x32_bf16 v[54:57], v[170:173], v[190:193], v[54:57]
	v_mfma_f32_16x16x32_bf16 v[50:53], v[178:181], v[190:193], v[50:53]
	v_mfma_f32_16x16x32_bf16 v[38:41], v[170:173], v[198:201], v[38:41]
	v_mfma_f32_16x16x32_bf16 v[34:37], v[178:181], v[198:201], v[34:37]
	v_mfma_f32_16x16x32_bf16 v[22:25], v[170:173], v[208:211], v[22:25]
	v_mfma_f32_16x16x32_bf16 v[18:21], v[178:181], v[208:211], v[18:21]
	v_mfma_f32_16x16x32_bf16 v[6:9], v[170:173], v[216:219], v[6:9]
	v_mfma_f32_16x16x32_bf16 v[2:5], v[178:181], v[216:219], v[2:5]
	v_mfma_f32_16x16x32_bf16 v[54:57], v[174:177], v[194:197], v[54:57]
	v_mfma_f32_16x16x32_bf16 v[50:53], v[186:189], v[194:197], v[50:53]
	v_mfma_f32_16x16x32_bf16 v[38:41], v[174:177], v[202:205], v[38:41]
	v_mfma_f32_16x16x32_bf16 v[34:37], v[186:189], v[202:205], v[34:37]
	v_mfma_f32_16x16x32_bf16 v[22:25], v[174:177], v[212:215], v[22:25]
	v_mfma_f32_16x16x32_bf16 v[18:21], v[186:189], v[212:215], v[18:21]
	v_mfma_f32_16x16x32_bf16 v[6:9], v[174:177], v[220:223], v[6:9]
	v_mfma_f32_16x16x32_bf16 v[2:5], v[186:189], v[220:223], v[2:5]
	s_setprio 0
	s_barrier
	s_add_i32 s15, 0, 0x18000
	s_add_i32 s25, 0, 0x1c000
	v_add_u32_e32 v166, s15, v157
	v_add_u32_e32 v184, s25, v157
	ds_read_b128 v[146:149], v166
	ds_read_b128 v[150:153], v166 offset:1024
	ds_read_b128 v[162:165], v166 offset:2048
	ds_read_b128 v[166:169], v166 offset:3072
	ds_read_b128 v[170:173], v184
	ds_read_b128 v[174:177], v184 offset:1024
	ds_read_b128 v[178:181], v184 offset:2048
	ds_read_b128 v[186:189], v184 offset:3072
	s_add_u32 s18, s64, 0x80000
	s_addc_u32 s19, s65, 0
	s_mov_b32 m0, s69
	v_lshl_add_u64 v[230:231], s[18:19], 0, v[134:135]
	ds_read_b128 v[190:193], v161 offset:32768
	ds_read_b128 v[194:197], v161 offset:33792
	ds_read_b128 v[198:201], v161 offset:34816
	ds_read_b128 v[202:205], v161 offset:35840
	ds_read_b128 v[208:211], v161 offset:36864
	ds_read_b128 v[212:215], v161 offset:37888
	ds_read_b128 v[216:219], v161 offset:38912
	ds_read_b128 v[220:223], v161 offset:39936
	global_load_lds_dwordx4 v[230:231], off
	v_lshl_add_u64 v[230:231], s[18:19], 0, v[136:137]
	s_mov_b32 m0, s70
	s_nop 0
	global_load_lds_dwordx4 v[230:231], off
	s_waitcnt vmcnt(8)
	s_waitcnt lgkmcnt(0)
	s_barrier
	s_setprio 1
	s_waitcnt lgkmcnt(0)
	v_mfma_f32_16x16x32_bf16 v[130:133], v[146:149], v[190:193], v[130:133]
	v_mfma_f32_16x16x32_bf16 v[126:129], v[162:165], v[190:193], v[126:129]
	v_mfma_f32_16x16x32_bf16 v[114:117], v[146:149], v[198:201], v[114:117]
	v_mfma_f32_16x16x32_bf16 v[110:113], v[162:165], v[198:201], v[110:113]
	v_mfma_f32_16x16x32_bf16 v[94:97], v[146:149], v[208:211], v[94:97]
	v_mfma_f32_16x16x32_bf16 v[90:93], v[162:165], v[208:211], v[90:93]
	v_mfma_f32_16x16x32_bf16 v[78:81], v[146:149], v[216:219], v[78:81]
	v_mfma_f32_16x16x32_bf16 v[74:77], v[162:165], v[216:219], v[74:77]
	v_mfma_f32_16x16x32_bf16 v[130:133], v[150:153], v[194:197], v[130:133]
	v_mfma_f32_16x16x32_bf16 v[126:129], v[166:169], v[194:197], v[126:129]
	v_mfma_f32_16x16x32_bf16 v[114:117], v[150:153], v[202:205], v[114:117]
	v_mfma_f32_16x16x32_bf16 v[110:113], v[166:169], v[202:205], v[110:113]
	v_mfma_f32_16x16x32_bf16 v[94:97], v[150:153], v[212:215], v[94:97]
	v_mfma_f32_16x16x32_bf16 v[90:93], v[166:169], v[212:215], v[90:93]
	v_mfma_f32_16x16x32_bf16 v[78:81], v[150:153], v[220:223], v[78:81]
	v_mfma_f32_16x16x32_bf16 v[74:77], v[166:169], v[220:223], v[74:77]
	s_setprio 0
	s_setprio 1
	v_mfma_f32_16x16x32_bf16 v[122:125], v[170:173], v[190:193], v[122:125]
	v_mfma_f32_16x16x32_bf16 v[118:121], v[178:181], v[190:193], v[118:121]
	v_mfma_f32_16x16x32_bf16 v[106:109], v[170:173], v[198:201], v[106:109]
	v_mfma_f32_16x16x32_bf16 v[102:105], v[178:181], v[198:201], v[102:105]
	v_mfma_f32_16x16x32_bf16 v[86:89], v[170:173], v[208:211], v[86:89]
	v_mfma_f32_16x16x32_bf16 v[82:85], v[178:181], v[208:211], v[82:85]
	v_mfma_f32_16x16x32_bf16 v[70:73], v[170:173], v[216:219], v[70:73]
	v_mfma_f32_16x16x32_bf16 v[66:69], v[178:181], v[216:219], v[66:69]
	v_mfma_f32_16x16x32_bf16 v[122:125], v[174:177], v[194:197], v[122:125]
	v_mfma_f32_16x16x32_bf16 v[118:121], v[186:189], v[194:197], v[118:121]
	v_mfma_f32_16x16x32_bf16 v[106:109], v[174:177], v[202:205], v[106:109]
	v_mfma_f32_16x16x32_bf16 v[102:105], v[186:189], v[202:205], v[102:105]
	v_mfma_f32_16x16x32_bf16 v[86:89], v[174:177], v[212:215], v[86:89]
	v_mfma_f32_16x16x32_bf16 v[82:85], v[186:189], v[212:215], v[82:85]
	v_mfma_f32_16x16x32_bf16 v[70:73], v[174:177], v[220:223], v[70:73]
	v_mfma_f32_16x16x32_bf16 v[66:69], v[186:189], v[220:223], v[66:69]
	s_setprio 0
	s_barrier
; #define PG8_STAGE(bufoff, gbase, voff) do { _Pragma("unroll") for (int _i = 0; _i < 2; ++_i) \
;         __builtin_amdgcn_global_load_lds((const unsigned*)((const char*)(gbase) + (voff)[_i]), (PG8_LAS unsigned*)(lds + (bufoff) + ldsw + _i * 8192), 16, 0, 0); } while (0)
; #define PG8_LDA(dst, b, h) do { _Pragma("unroll") for (int m = 0; m < 4; ++m) _Pragma("unroll") for (int k = 0; k < 2; ++k) dst[m][k] = *(const PG8_LAS bf16x8*)(lds + PG8_SA(b, h) + aoff + m * 2048 + k * 1024); } while (0)
; #define PG8_MMA(ai, bj, At, Bt) do { __builtin_amdgcn_s_setprio(1); _Pragma("unroll") for (int m = 0; m < 4; ++m) _Pragma("unroll") for (int n = 0; n < 2; ++n) _Pragma("unroll") for (int k = 0; k < 2; ++k) \
;         acc[ai][bj][m][n] = __builtin_amdgcn_mfma_f32_16x16x32_bf16(Bt[n][k], At[m][k], acc[ai][bj][m][n], 0, 0, 0); __builtin_amdgcn_s_setprio(0); } while (0)
; #define PG8_WAIT_V(n) asm volatile("s_waitcnt vmcnt(" #n ")" ::: "memory")
; #define PG8_WAIT_L(n) asm volatile("s_waitcnt lgkmcnt(" #n ")" ::: "memory")
; #define PG8_BAR __builtin_amdgcn_s_barrier()
; #define PG8_SCHED __builtin_amdgcn_sched_barrier(0)
; template <class Epi, class Sched, bool ALIGN_EPI = false, bool SP2 = false>
; __device__ __forceinline__ void gemm_phase(PG8_LAS unsigned char* lds, const Gemm g, const Sched& S, const Epi& E) {
;     ...
;         for (int t = 0; t < nt; t += 2) {
;             const bool last = (t == nt - 2);
;             const char* a1 = cA + (size_t)(t + 1) * kstep;
;             const char* a2 = last ? nA : cA + (size_t)(t + 2) * kstep; const char* b2 = last ? nB : cB + (size_t)(t + 2) * kstep;
;             const char* a3 = a2 + kstep; const char* b3 = b2 + kstep;
;     ...
;             PG8_LDA(At, 1, 1); PG8_STAGE(PG8_SB(1, 0), b3, voffB); PG8_STAGE(PG8_SB(1, 1), b3 + hstep, voffB); PG8_STAGE(PG8_SA(1, 0), a3, voffA);
;             PG8_WAIT_V(8); PG8_WAIT_L(0); PG8_BAR; PG8_MMA(1, 0, At, B0); PG8_MMA(1, 1, At, B1); PG8_BAR; PG8_SCHED;
	s_add_i32 s15, s15, s67
	v_lshl_add_u64 v[154:155], v[154:155], 0, s[22:23]
	s_mov_b32 m0, s15
	ds_read_b128 v[190:193], v161 offset:49152
	ds_read_b128 v[194:197], v161 offset:50176
	ds_read_b128 v[198:201], v161 offset:51200
	ds_read_b128 v[202:205], v161 offset:52224
	ds_read_b128 v[208:211], v161 offset:53248
	ds_read_b128 v[212:215], v161 offset:54272
	ds_read_b128 v[216:219], v161 offset:55296
	ds_read_b128 v[220:223], v161 offset:56320
	global_load_lds_dwordx4 v[154:155], off
	s_add_i32 m0, s15, 0x2000
	s_add_u32 s18, s62, 0x80080
	v_lshl_add_u64 v[154:155], v[182:183], 0, s[22:23]
	s_addc_u32 s19, s63, 0
	s_add_i32 s15, s25, s67
	global_load_lds_dwordx4 v[154:155], off
	v_lshl_add_u64 v[154:155], s[18:19], 0, v[0:1]
	s_mov_b32 m0, s15
	s_nop 0
	global_load_lds_dwordx4 v[154:155], off
	v_lshl_add_u64 v[154:155], s[18:19], 0, v[138:139]
	s_add_i32 m0, s15, 0x2000
	s_nop 0
	global_load_lds_dwordx4 v[154:155], off
	v_lshl_add_u64 v[154:155], v[224:225], 0, s[22:23]
	s_mov_b32 m0, s75
	s_nop 0
	global_load_lds_dwordx4 v[154:155], off
	v_lshl_add_u64 v[154:155], v[226:227], 0, s[22:23]
	s_mov_b32 m0, s76
	s_nop 0
	global_load_lds_dwordx4 v[154:155], off
	s_waitcnt vmcnt(8)
	s_waitcnt lgkmcnt(0)
	s_barrier
	s_setprio 1
	s_waitcnt lgkmcnt(0)
	v_mfma_f32_16x16x32_bf16 v[62:65], v[146:149], v[190:193], v[62:65]
	v_mfma_f32_16x16x32_bf16 v[58:61], v[162:165], v[190:193], v[58:61]
	v_mfma_f32_16x16x32_bf16 v[46:49], v[146:149], v[198:201], v[46:49]
	v_mfma_f32_16x16x32_bf16 v[42:45], v[162:165], v[198:201], v[42:45]
	v_mfma_f32_16x16x32_bf16 v[30:33], v[146:149], v[208:211], v[30:33]
	v_mfma_f32_16x16x32_bf16 v[26:29], v[162:165], v[208:211], v[26:29]
	v_mfma_f32_16x16x32_bf16 v[14:17], v[146:149], v[216:219], v[14:17]
	v_mfma_f32_16x16x32_bf16 v[10:13], v[162:165], v[216:219], v[10:13]
	v_mfma_f32_16x16x32_bf16 v[62:65], v[150:153], v[194:197], v[62:65]
	v_mfma_f32_16x16x32_bf16 v[58:61], v[166:169], v[194:197], v[58:61]
	v_mfma_f32_16x16x32_bf16 v[46:49], v[150:153], v[202:205], v[46:49]
	v_mfma_f32_16x16x32_bf16 v[42:45], v[166:169], v[202:205], v[42:45]
	v_mfma_f32_16x16x32_bf16 v[30:33], v[150:153], v[212:215], v[30:33]
	v_mfma_f32_16x16x32_bf16 v[26:29], v[166:169], v[212:215], v[26:29]
	v_mfma_f32_16x16x32_bf16 v[14:17], v[150:153], v[220:223], v[14:17]
	v_mfma_f32_16x16x32_bf16 v[10:13], v[166:169], v[220:223], v[10:13]
	s_setprio 0
	s_setprio 1
	v_mfma_f32_16x16x32_bf16 v[54:57], v[170:173], v[190:193], v[54:57]
	v_mfma_f32_16x16x32_bf16 v[50:53], v[178:181], v[190:193], v[50:53]
	v_mfma_f32_16x16x32_bf16 v[38:41], v[170:173], v[198:201], v[38:41]
	v_mfma_f32_16x16x32_bf16 v[34:37], v[178:181], v[198:201], v[34:37]
	v_mfma_f32_16x16x32_bf16 v[22:25], v[170:173], v[208:211], v[22:25]
	v_mfma_f32_16x16x32_bf16 v[18:21], v[178:181], v[208:211], v[18:21]
	v_mfma_f32_16x16x32_bf16 v[6:9], v[170:173], v[216:219], v[6:9]
	v_mfma_f32_16x16x32_bf16 v[2:5], v[178:181], v[216:219], v[2:5]
	s_add_u32 s12, s12, 0x100
	s_addc_u32 s14, s14, 0
	s_add_u32 s60, s60, 0x100
	s_addc_u32 s61, s61, 0
	s_mov_b32 s15, s16
	s_add_i32 s16, s15, 2
	s_add_u32 s18, s60, 0xfff80080
	s_addc_u32 s19, s61, -1
	s_add_i32 s25, 0, 0x10000
	s_cmp_eq_u32 s77, s15
	s_cselect_b32 s65, s2, s19
	s_cselect_b32 s64, s3, s18
	v_add_u32_e32 v154, s25, v157
	s_cselect_b32 s63, s8, s14
	s_cselect_b32 s62, s9, s12
	s_cmp_ge_u32 s15, s74
	v_mfma_f32_16x16x32_bf16 v[54:57], v[174:177], v[194:197], v[54:57]
	v_mfma_f32_16x16x32_bf16 v[50:53], v[186:189], v[194:197], v[50:53]
	v_mfma_f32_16x16x32_bf16 v[38:41], v[174:177], v[202:205], v[38:41]
	v_mfma_f32_16x16x32_bf16 v[34:37], v[186:189], v[202:205], v[34:37]
	v_mfma_f32_16x16x32_bf16 v[22:25], v[174:177], v[212:215], v[22:25]
	v_mfma_f32_16x16x32_bf16 v[18:21], v[186:189], v[212:215], v[18:21]
	v_mfma_f32_16x16x32_bf16 v[6:9], v[174:177], v[220:223], v[6:9]
	v_mfma_f32_16x16x32_bf16 v[2:5], v[186:189], v[220:223], v[2:5]
	s_setprio 0
	s_barrier
	s_cbranch_scc0 .Lmy_rot2
	s_and_b64 vcc, exec, s[46:47]
	s_cbranch_vccz .LBB0_1204
	s_barrier

; #define PG8_STAGE(bufoff, gbase, voff) do { _Pragma("unroll") for (int _i = 0; _i < 2; ++_i) \
;         __builtin_amdgcn_global_load_lds((const unsigned*)((const char*)(gbase) + (voff)[_i]), (PG8_LAS unsigned*)(lds + (bufoff) + ldsw + _i * 8192), 16, 0, 0); } while (0)
; #define PG8_LDA(dst, b, h) do { _Pragma("unroll") for (int m = 0; m < 4; ++m) _Pragma("unroll") for (int k = 0; k < 2; ++k) dst[m][k] = *(const PG8_LAS bf16x8*)(lds + PG8_SA(b, h) + aoff + m * 2048 + k * 1024); } while (0)
; #define PG8_LDB(dst, b, h) do { _Pragma("unroll") for (int n = 0; n < 2; ++n) _Pragma("unroll") for (int k = 0; k < 2; ++k) dst[n][k] = *(const PG8_LAS bf16x8*)(lds + PG8_SB(b, h) + boff + n * 2048 + k * 1024); } while (0)
; #define PG8_MMA(ai, bj, At, Bt) do { __builtin_amdgcn_s_setprio(1); _Pragma("unroll") for (int m = 0; m < 4; ++m) _Pragma("unroll") for (int n = 0; n < 2; ++n) _Pragma("unroll") for (int k = 0; k < 2; ++k) \
;         acc[ai][bj][m][n] = __builtin_amdgcn_mfma_f32_16x16x32_bf16(Bt[n][k], At[m][k], acc[ai][bj][m][n], 0, 0, 0); __builtin_amdgcn_s_setprio(0); } while (0)
; #define PG8_WAIT_V(n) asm volatile("s_waitcnt vmcnt(" #n ")" ::: "memory")
; #define PG8_WAIT_L(n) asm volatile("s_waitcnt lgkmcnt(" #n ")" ::: "memory")
; #define PG8_BAR __builtin_amdgcn_s_barrier()
; #define PG8_SCHED __builtin_amdgcn_sched_barrier(0)
; template <class Epi, class Sched, bool ALIGN_EPI = false, bool SP2 = false>
; __device__ __forceinline__ void gemm_phase(PG8_LAS unsigned char* lds, const Gemm g, const Sched& S, const Epi& E) {
;     ...
;             PG8_LDB(B0, 0, 0); PG8_LDB(B1, 0, 1); PG8_SCHED; PG8_LDA(At, 0, 0); PG8_STAGE(PG8_SA(1, 1), a1 + hstep, voffA);
;             PG8_WAIT_V(8); PG8_WAIT_L(0); PG8_BAR; PG8_MMA(0, 0, At, B0); PG8_MMA(0, 1, At, B1); PG8_BAR; PG8_SCHED;
;             PG8_LDA(At, 0, 1); PG8_STAGE(PG8_SB(0, 0), b2, voffB); PG8_STAGE(PG8_SB(0, 1), b2 + hstep, voffB); PG8_STAGE(PG8_SA(0, 0), a2, voffA);
;             PG8_WAIT_V(8); PG8_WAIT_L(0); PG8_BAR; PG8_MMA(1, 0, At, B0); PG8_MMA(1, 1, At, B1); PG8_BAR; PG8_SCHED;
.Lmy_rot1:
	s_add_i32 s41, 0, 0x14000
	ds_read_b128 v[146:149], v154
	ds_read_b128 v[150:153], v154 offset:1024
	ds_read_b128 v[160:163], v154 offset:2048
	ds_read_b128 v[164:167], v154 offset:3072
	v_add_u32_e32 v154, s41, v157
	ds_read_b128 v[168:171], v154
	ds_read_b128 v[172:175], v154 offset:1024
	ds_read_b128 v[176:179], v154 offset:2048
	ds_read_b128 v[180:183], v154 offset:3072
	v_lshl_add_u64 v[154:155], s[0:1], 0, v[144:145]
	s_add_i32 m0, s16, 0xc000
	ds_read_b128 v[186:189], v159
	ds_read_b128 v[190:193], v159 offset:1024
	ds_read_b128 v[194:197], v159 offset:2048
	ds_read_b128 v[198:201], v159 offset:3072
	ds_read_b128 v[202:205], v159 offset:4096
	ds_read_b128 v[208:211], v159 offset:5120
	ds_read_b128 v[212:215], v159 offset:6144
	ds_read_b128 v[216:219], v159 offset:7168
	global_load_lds_dwordx4 v[154:155], off
	v_lshl_add_u64 v[154:155], s[0:1], 0, v[140:141]
	s_add_i32 m0, s16, 0xe000
	s_nop 0
	global_load_lds_dwordx4 v[154:155], off
	s_waitcnt vmcnt(8)
	s_waitcnt lgkmcnt(0)
	s_barrier
	s_setprio 1
	s_waitcnt lgkmcnt(0)
	v_mfma_f32_16x16x32_bf16 v[130:133], v[146:149], v[186:189], v[130:133]
	v_mfma_f32_16x16x32_bf16 v[126:129], v[160:163], v[186:189], v[126:129]
	v_mfma_f32_16x16x32_bf16 v[114:117], v[146:149], v[194:197], v[114:117]
	v_mfma_f32_16x16x32_bf16 v[110:113], v[160:163], v[194:197], v[110:113]
	v_mfma_f32_16x16x32_bf16 v[94:97], v[146:149], v[202:205], v[94:97]
	v_mfma_f32_16x16x32_bf16 v[90:93], v[160:163], v[202:205], v[90:93]
	v_mfma_f32_16x16x32_bf16 v[78:81], v[146:149], v[212:215], v[78:81]
	v_mfma_f32_16x16x32_bf16 v[74:77], v[160:163], v[212:215], v[74:77]
	v_mfma_f32_16x16x32_bf16 v[130:133], v[150:153], v[190:193], v[130:133]
	v_mfma_f32_16x16x32_bf16 v[126:129], v[164:167], v[190:193], v[126:129]
	v_mfma_f32_16x16x32_bf16 v[114:117], v[150:153], v[198:201], v[114:117]
	v_mfma_f32_16x16x32_bf16 v[110:113], v[164:167], v[198:201], v[110:113]
	v_mfma_f32_16x16x32_bf16 v[94:97], v[150:153], v[208:211], v[94:97]
	v_mfma_f32_16x16x32_bf16 v[90:93], v[164:167], v[208:211], v[90:93]
	v_mfma_f32_16x16x32_bf16 v[78:81], v[150:153], v[216:219], v[78:81]
	v_mfma_f32_16x16x32_bf16 v[74:77], v[164:167], v[216:219], v[74:77]
	s_setprio 0
	s_setprio 1
	v_mfma_f32_16x16x32_bf16 v[122:125], v[168:171], v[186:189], v[122:125]
	v_mfma_f32_16x16x32_bf16 v[118:121], v[176:179], v[186:189], v[118:121]
	v_mfma_f32_16x16x32_bf16 v[106:109], v[168:171], v[194:197], v[106:109]
	v_mfma_f32_16x16x32_bf16 v[102:105], v[176:179], v[194:197], v[102:105]
	v_mfma_f32_16x16x32_bf16 v[86:89], v[168:171], v[202:205], v[86:89]
	v_mfma_f32_16x16x32_bf16 v[82:85], v[176:179], v[202:205], v[82:85]
	v_mfma_f32_16x16x32_bf16 v[70:73], v[168:171], v[212:215], v[70:73]
	v_mfma_f32_16x16x32_bf16 v[66:69], v[176:179], v[212:215], v[66:69]
	v_mfma_f32_16x16x32_bf16 v[122:125], v[172:175], v[190:193], v[122:125]
	v_mfma_f32_16x16x32_bf16 v[118:121], v[180:183], v[190:193], v[118:121]
	v_mfma_f32_16x16x32_bf16 v[106:109], v[172:175], v[198:201], v[106:109]
	v_mfma_f32_16x16x32_bf16 v[102:105], v[180:183], v[198:201], v[102:105]
	v_mfma_f32_16x16x32_bf16 v[86:89], v[172:175], v[208:211], v[86:89]
	v_mfma_f32_16x16x32_bf16 v[82:85], v[180:183], v[208:211], v[82:85]
	v_mfma_f32_16x16x32_bf16 v[70:73], v[172:175], v[216:219], v[70:73]
	v_mfma_f32_16x16x32_bf16 v[66:69], v[180:183], v[216:219], v[66:69]
	s_setprio 0
	s_barrier
	s_add_i32 s51, s51, s10
	v_lshl_add_u64 v[154:155], s[42:43], 0, v[0:1]
	s_mov_b32 m0, s51
	ds_read_b128 v[186:189], v159 offset:16384
	ds_read_b128 v[190:193], v159 offset:17408
	ds_read_b128 v[194:197], v159 offset:18432
	ds_read_b128 v[198:201], v159 offset:19456
	ds_read_b128 v[202:205], v159 offset:20480
	ds_read_b128 v[208:211], v159 offset:21504
	ds_read_b128 v[212:215], v159 offset:22528
	ds_read_b128 v[216:219], v159 offset:23552
	global_load_lds_dwordx4 v[154:155], off
	s_add_i32 m0, s51, 0x2000
	s_add_u32 s60, s42, 0x80000
	v_lshl_add_u64 v[220:221], s[42:43], 0, v[138:139]
	s_addc_u32 s61, s43, 0
	s_add_i32 s41, s41, s10
	global_load_lds_dwordx4 v[220:221], off
	v_lshl_add_u64 v[222:223], s[60:61], 0, v[0:1]
	s_mov_b32 m0, s41
	v_lshl_add_u64 v[224:225], s[58:59], 0, v[136:137]
	global_load_lds_dwordx4 v[222:223], off
	v_lshl_add_u64 v[222:223], s[60:61], 0, v[138:139]
	s_add_i32 m0, s41, 0x2000
	s_nop 0
	global_load_lds_dwordx4 v[222:223], off
	v_lshl_add_u64 v[222:223], s[58:59], 0, v[134:135]
	s_mov_b32 m0, s16
	s_nop 0
	global_load_lds_dwordx4 v[222:223], off
	s_mov_b32 m0, s17
	s_nop 0
	global_load_lds_dwordx4 v[224:225], off
	s_waitcnt vmcnt(8)
	s_waitcnt lgkmcnt(0)
	s_barrier
; #define PG8_STAGE(bufoff, gbase, voff) do { _Pragma("unroll") for (int _i = 0; _i < 2; ++_i) \
;         __builtin_amdgcn_global_load_lds((const unsigned*)((const char*)(gbase) + (voff)[_i]), (PG8_LAS unsigned*)(lds + (bufoff) + ldsw + _i * 8192), 16, 0, 0); } while (0)
; #define PG8_LDA(dst, b, h) do { _Pragma("unroll") for (int m = 0; m < 4; ++m) _Pragma("unroll") for (int k = 0; k < 2; ++k) dst[m][k] = *(const PG8_LAS bf16x8*)(lds + PG8_SA(b, h) + aoff + m * 2048 + k * 1024); } while (0)
; #define PG8_LDB(dst, b, h) do { _Pragma("unroll") for (int n = 0; n < 2; ++n) _Pragma("unroll") for (int k = 0; k < 2; ++k) dst[n][k] = *(const PG8_LAS bf16x8*)(lds + PG8_SB(b, h) + boff + n * 2048 + k * 1024); } while (0)
; #define PG8_MMA(ai, bj, At, Bt) do { __builtin_amdgcn_s_setprio(1); _Pragma("unroll") for (int m = 0; m < 4; ++m) _Pragma("unroll") for (int n = 0; n < 2; ++n) _Pragma("unroll") for (int k = 0; k < 2; ++k) \
;         acc[ai][bj][m][n] = __builtin_amdgcn_mfma_f32_16x16x32_bf16(Bt[n][k], At[m][k], acc[ai][bj][m][n], 0, 0, 0); __builtin_amdgcn_s_setprio(0); } while (0)
; #define PG8_WAIT_V(n) asm volatile("s_waitcnt vmcnt(" #n ")" ::: "memory")
; #define PG8_WAIT_L(n) asm volatile("s_waitcnt lgkmcnt(" #n ")" ::: "memory")
; #define PG8_BAR __builtin_amdgcn_s_barrier()
; #define PG8_SCHED __builtin_amdgcn_sched_barrier(0)
; template <class Epi, class Sched, bool ALIGN_EPI = false, bool SP2 = false>
; __device__ __forceinline__ void gemm_phase(PG8_LAS unsigned char* lds, const Gemm g, const Sched& S, const Epi& E) {
;     ...
;             PG8_WAIT_V(8); PG8_WAIT_L(0); PG8_BAR; PG8_MMA(1, 0, At, B0); PG8_MMA(1, 1, At, B1); PG8_BAR; PG8_SCHED;
;             PG8_LDB(B0, 1, 0); PG8_LDB(B1, 1, 1); PG8_SCHED; PG8_LDA(At, 1, 0); PG8_STAGE(PG8_SA(0, 1), a2 + hstep, voffA);
;             PG8_WAIT_V(8); PG8_WAIT_L(0); PG8_BAR; PG8_MMA(0, 0, At, B0); PG8_MMA(0, 1, At, B1); PG8_BAR; PG8_SCHED;
	s_setprio 1
	s_waitcnt lgkmcnt(0)
	v_mfma_f32_16x16x32_bf16 v[62:65], v[146:149], v[186:189], v[62:65]
	v_mfma_f32_16x16x32_bf16 v[58:61], v[160:163], v[186:189], v[58:61]
	v_mfma_f32_16x16x32_bf16 v[46:49], v[146:149], v[194:197], v[46:49]
	v_mfma_f32_16x16x32_bf16 v[42:45], v[160:163], v[194:197], v[42:45]
	v_mfma_f32_16x16x32_bf16 v[30:33], v[146:149], v[202:205], v[30:33]
	v_mfma_f32_16x16x32_bf16 v[26:29], v[160:163], v[202:205], v[26:29]
	v_mfma_f32_16x16x32_bf16 v[14:17], v[146:149], v[212:215], v[14:17]
	v_mfma_f32_16x16x32_bf16 v[10:13], v[160:163], v[212:215], v[10:13]
	v_mfma_f32_16x16x32_bf16 v[62:65], v[150:153], v[190:193], v[62:65]
	v_mfma_f32_16x16x32_bf16 v[58:61], v[164:167], v[190:193], v[58:61]
	v_mfma_f32_16x16x32_bf16 v[46:49], v[150:153], v[198:201], v[46:49]
	v_mfma_f32_16x16x32_bf16 v[42:45], v[164:167], v[198:201], v[42:45]
	v_mfma_f32_16x16x32_bf16 v[30:33], v[150:153], v[208:211], v[30:33]
	v_mfma_f32_16x16x32_bf16 v[26:29], v[164:167], v[208:211], v[26:29]
	v_mfma_f32_16x16x32_bf16 v[14:17], v[150:153], v[216:219], v[14:17]
	v_mfma_f32_16x16x32_bf16 v[10:13], v[164:167], v[216:219], v[10:13]
	s_setprio 0
	s_setprio 1
	v_mfma_f32_16x16x32_bf16 v[54:57], v[168:171], v[186:189], v[54:57]
	v_mfma_f32_16x16x32_bf16 v[50:53], v[176:179], v[186:189], v[50:53]
	v_mfma_f32_16x16x32_bf16 v[38:41], v[168:171], v[194:197], v[38:41]
	v_mfma_f32_16x16x32_bf16 v[34:37], v[176:179], v[194:197], v[34:37]
	v_mfma_f32_16x16x32_bf16 v[22:25], v[168:171], v[202:205], v[22:25]
	v_mfma_f32_16x16x32_bf16 v[18:21], v[176:179], v[202:205], v[18:21]
	v_mfma_f32_16x16x32_bf16 v[6:9], v[168:171], v[212:215], v[6:9]
	v_mfma_f32_16x16x32_bf16 v[2:5], v[176:179], v[212:215], v[2:5]
	v_mfma_f32_16x16x32_bf16 v[54:57], v[172:175], v[190:193], v[54:57]
	v_mfma_f32_16x16x32_bf16 v[50:53], v[180:183], v[190:193], v[50:53]
	v_mfma_f32_16x16x32_bf16 v[38:41], v[172:175], v[198:201], v[38:41]
	v_mfma_f32_16x16x32_bf16 v[34:37], v[180:183], v[198:201], v[34:37]
	v_mfma_f32_16x16x32_bf16 v[22:25], v[172:175], v[208:211], v[22:25]
	v_mfma_f32_16x16x32_bf16 v[18:21], v[180:183], v[208:211], v[18:21]
	v_mfma_f32_16x16x32_bf16 v[6:9], v[172:175], v[216:219], v[6:9]
	v_mfma_f32_16x16x32_bf16 v[2:5], v[180:183], v[216:219], v[2:5]
	s_setprio 0
	s_barrier
	s_add_i32 s41, 0, 0x18000
	s_add_i32 s51, 0, 0x1c000
	v_add_u32_e32 v164, s41, v157
	v_add_u32_e32 v180, s51, v157
	ds_read_b128 v[146:149], v164
	ds_read_b128 v[150:153], v164 offset:1024
	ds_read_b128 v[160:163], v164 offset:2048
	ds_read_b128 v[164:167], v164 offset:3072
	ds_read_b128 v[168:171], v180
	ds_read_b128 v[172:175], v180 offset:1024
	ds_read_b128 v[176:179], v180 offset:2048
	ds_read_b128 v[180:183], v180 offset:3072
	s_add_u32 s58, s58, 0x80000
	s_addc_u32 s59, s59, 0
	s_mov_b32 m0, s25
	v_lshl_add_u64 v[226:227], s[58:59], 0, v[134:135]
	ds_read_b128 v[186:189], v159 offset:32768
	ds_read_b128 v[190:193], v159 offset:33792
	ds_read_b128 v[194:197], v159 offset:34816
	ds_read_b128 v[198:201], v159 offset:35840
	ds_read_b128 v[202:205], v159 offset:36864
	ds_read_b128 v[208:211], v159 offset:37888
	ds_read_b128 v[212:215], v159 offset:38912
	ds_read_b128 v[216:219], v159 offset:39936
	global_load_lds_dwordx4 v[226:227], off
	v_lshl_add_u64 v[226:227], s[58:59], 0, v[136:137]
	s_mov_b32 m0, s30
	s_nop 0
	global_load_lds_dwordx4 v[226:227], off
	s_waitcnt vmcnt(8)
	s_waitcnt lgkmcnt(0)
	s_barrier
	s_setprio 1
	s_waitcnt lgkmcnt(0)
	v_mfma_f32_16x16x32_bf16 v[130:133], v[146:149], v[186:189], v[130:133]
	v_mfma_f32_16x16x32_bf16 v[126:129], v[160:163], v[186:189], v[126:129]
	v_mfma_f32_16x16x32_bf16 v[114:117], v[146:149], v[194:197], v[114:117]
	v_mfma_f32_16x16x32_bf16 v[110:113], v[160:163], v[194:197], v[110:113]
	v_mfma_f32_16x16x32_bf16 v[94:97], v[146:149], v[202:205], v[94:97]
	v_mfma_f32_16x16x32_bf16 v[90:93], v[160:163], v[202:205], v[90:93]
	v_mfma_f32_16x16x32_bf16 v[78:81], v[146:149], v[212:215], v[78:81]
	v_mfma_f32_16x16x32_bf16 v[74:77], v[160:163], v[212:215], v[74:77]
	v_mfma_f32_16x16x32_bf16 v[130:133], v[150:153], v[190:193], v[130:133]
	v_mfma_f32_16x16x32_bf16 v[126:129], v[164:167], v[190:193], v[126:129]
	v_mfma_f32_16x16x32_bf16 v[114:117], v[150:153], v[198:201], v[114:117]
	v_mfma_f32_16x16x32_bf16 v[110:113], v[164:167], v[198:201], v[110:113]
	v_mfma_f32_16x16x32_bf16 v[94:97], v[150:153], v[208:211], v[94:97]
	v_mfma_f32_16x16x32_bf16 v[90:93], v[164:167], v[208:211], v[90:93]
	v_mfma_f32_16x16x32_bf16 v[78:81], v[150:153], v[216:219], v[78:81]
	v_mfma_f32_16x16x32_bf16 v[74:77], v[164:167], v[216:219], v[74:77]
	s_setprio 0
	s_setprio 1
	v_mfma_f32_16x16x32_bf16 v[122:125], v[168:171], v[186:189], v[122:125]
	v_mfma_f32_16x16x32_bf16 v[118:121], v[176:179], v[186:189], v[118:121]
	v_mfma_f32_16x16x32_bf16 v[106:109], v[168:171], v[194:197], v[106:109]
	v_mfma_f32_16x16x32_bf16 v[102:105], v[176:179], v[194:197], v[102:105]
	v_mfma_f32_16x16x32_bf16 v[86:89], v[168:171], v[202:205], v[86:89]
	v_mfma_f32_16x16x32_bf16 v[82:85], v[176:179], v[202:205], v[82:85]
	v_mfma_f32_16x16x32_bf16 v[70:73], v[168:171], v[212:215], v[70:73]
	v_mfma_f32_16x16x32_bf16 v[66:69], v[176:179], v[212:215], v[66:69]
	v_mfma_f32_16x16x32_bf16 v[122:125], v[172:175], v[190:193], v[122:125]
	v_mfma_f32_16x16x32_bf16 v[118:121], v[180:183], v[190:193], v[118:121]
	v_mfma_f32_16x16x32_bf16 v[106:109], v[172:175], v[198:201], v[106:109]
	v_mfma_f32_16x16x32_bf16 v[102:105], v[180:183], v[198:201], v[102:105]
	v_mfma_f32_16x16x32_bf16 v[86:89], v[172:175], v[208:211], v[86:89]
	v_mfma_f32_16x16x32_bf16 v[82:85], v[180:183], v[208:211], v[82:85]
	v_mfma_f32_16x16x32_bf16 v[70:73], v[172:175], v[216:219], v[70:73]
	v_mfma_f32_16x16x32_bf16 v[66:69], v[180:183], v[216:219], v[66:69]
	s_setprio 0
	s_barrier
; #define PG8_STAGE(bufoff, gbase, voff) do { _Pragma("unroll") for (int _i = 0; _i < 2; ++_i) \
;         __builtin_amdgcn_global_load_lds((const unsigned*)((const char*)(gbase) + (voff)[_i]), (PG8_LAS unsigned*)(lds + (bufoff) + ldsw + _i * 8192), 16, 0, 0); } while (0)
; #define PG8_LDA(dst, b, h) do { _Pragma("unroll") for (int m = 0; m < 4; ++m) _Pragma("unroll") for (int k = 0; k < 2; ++k) dst[m][k] = *(const PG8_LAS bf16x8*)(lds + PG8_SA(b, h) + aoff + m * 2048 + k * 1024); } while (0)
; #define PG8_MMA(ai, bj, At, Bt) do { __builtin_amdgcn_s_setprio(1); _Pragma("unroll") for (int m = 0; m < 4; ++m) _Pragma("unroll") for (int n = 0; n < 2; ++n) _Pragma("unroll") for (int k = 0; k < 2; ++k) \
;         acc[ai][bj][m][n] = __builtin_amdgcn_mfma_f32_16x16x32_bf16(Bt[n][k], At[m][k], acc[ai][bj][m][n], 0, 0, 0); __builtin_amdgcn_s_setprio(0); } while (0)
; #define PG8_WAIT_V(n) asm volatile("s_waitcnt vmcnt(" #n ")" ::: "memory")
; #define PG8_WAIT_L(n) asm volatile("s_waitcnt lgkmcnt(" #n ")" ::: "memory")
; #define PG8_BAR __builtin_amdgcn_s_barrier()
; #define PG8_SCHED __builtin_amdgcn_sched_barrier(0)
; template <class Epi, class Sched, bool ALIGN_EPI = false, bool SP2 = false>
; __device__ __forceinline__ void gemm_phase(PG8_LAS unsigned char* lds, const Gemm g, const Sched& S, const Epi& E) {
;     ...
;         for (int t = 0; t < nt; t += 2) {
;             const bool last = (t == nt - 2);
;             const char* a1 = cA + (size_t)(t + 1) * kstep;
;             const char* a2 = last ? nA : cA + (size_t)(t + 2) * kstep; const char* b2 = last ? nB : cB + (size_t)(t + 2) * kstep;
;             const char* a3 = a2 + kstep; const char* b3 = b2 + kstep;
;     ...
;             PG8_LDA(At, 1, 1); PG8_STAGE(PG8_SB(1, 0), b3, voffB); PG8_STAGE(PG8_SB(1, 1), b3 + hstep, voffB); PG8_STAGE(PG8_SA(1, 0), a3, voffA);
;             PG8_WAIT_V(8); PG8_WAIT_L(0); PG8_BAR; PG8_MMA(1, 0, At, B0); PG8_MMA(1, 1, At, B1); PG8_BAR; PG8_SCHED;
	s_add_i32 s41, s41, s10
	v_lshl_add_u64 v[154:155], v[154:155], 0, s[22:23]
	s_mov_b32 m0, s41
	ds_read_b128 v[186:189], v159 offset:49152
	ds_read_b128 v[190:193], v159 offset:50176
	ds_read_b128 v[194:197], v159 offset:51200
	ds_read_b128 v[198:201], v159 offset:52224
	ds_read_b128 v[202:205], v159 offset:53248
	ds_read_b128 v[208:211], v159 offset:54272
	ds_read_b128 v[212:215], v159 offset:55296
	ds_read_b128 v[216:219], v159 offset:56320
	global_load_lds_dwordx4 v[154:155], off
	s_add_i32 m0, s41, 0x2000
	s_add_u32 s42, s42, 0x80080
	v_lshl_add_u64 v[154:155], v[220:221], 0, s[22:23]
	s_addc_u32 s43, s43, 0
	s_add_i32 s41, s51, s10
	global_load_lds_dwordx4 v[154:155], off
	v_lshl_add_u64 v[154:155], s[42:43], 0, v[0:1]
	s_mov_b32 m0, s41
	s_nop 0
	global_load_lds_dwordx4 v[154:155], off
	v_lshl_add_u64 v[154:155], s[42:43], 0, v[138:139]
	s_add_i32 m0, s41, 0x2000
	s_nop 0
	global_load_lds_dwordx4 v[154:155], off
	v_lshl_add_u64 v[154:155], v[222:223], 0, s[22:23]
	s_mov_b32 m0, s9
	s_nop 0
	global_load_lds_dwordx4 v[154:155], off
	v_lshl_add_u64 v[154:155], v[224:225], 0, s[22:23]
	s_mov_b32 m0, s15
	s_nop 0
	global_load_lds_dwordx4 v[154:155], off
	s_waitcnt vmcnt(8)
	s_waitcnt lgkmcnt(0)
	s_barrier
	s_setprio 1
	s_waitcnt lgkmcnt(0)
	v_mfma_f32_16x16x32_bf16 v[62:65], v[146:149], v[186:189], v[62:65]
	v_mfma_f32_16x16x32_bf16 v[58:61], v[160:163], v[186:189], v[58:61]
	v_mfma_f32_16x16x32_bf16 v[46:49], v[146:149], v[194:197], v[46:49]
	v_mfma_f32_16x16x32_bf16 v[42:45], v[160:163], v[194:197], v[42:45]
	v_mfma_f32_16x16x32_bf16 v[30:33], v[146:149], v[202:205], v[30:33]
	v_mfma_f32_16x16x32_bf16 v[26:29], v[160:163], v[202:205], v[26:29]
	v_mfma_f32_16x16x32_bf16 v[14:17], v[146:149], v[212:215], v[14:17]
	v_mfma_f32_16x16x32_bf16 v[10:13], v[160:163], v[212:215], v[10:13]
	v_mfma_f32_16x16x32_bf16 v[62:65], v[150:153], v[190:193], v[62:65]
	v_mfma_f32_16x16x32_bf16 v[58:61], v[164:167], v[190:193], v[58:61]
	v_mfma_f32_16x16x32_bf16 v[46:49], v[150:153], v[198:201], v[46:49]
	v_mfma_f32_16x16x32_bf16 v[42:45], v[164:167], v[198:201], v[42:45]
	v_mfma_f32_16x16x32_bf16 v[30:33], v[150:153], v[208:211], v[30:33]
	v_mfma_f32_16x16x32_bf16 v[26:29], v[164:167], v[208:211], v[26:29]
	v_mfma_f32_16x16x32_bf16 v[14:17], v[150:153], v[216:219], v[14:17]
	v_mfma_f32_16x16x32_bf16 v[10:13], v[164:167], v[216:219], v[10:13]
	s_setprio 0
	s_setprio 1
	v_mfma_f32_16x16x32_bf16 v[54:57], v[168:171], v[186:189], v[54:57]
	v_mfma_f32_16x16x32_bf16 v[50:53], v[176:179], v[186:189], v[50:53]
	v_mfma_f32_16x16x32_bf16 v[38:41], v[168:171], v[194:197], v[38:41]
	v_mfma_f32_16x16x32_bf16 v[34:37], v[176:179], v[194:197], v[34:37]
	v_mfma_f32_16x16x32_bf16 v[22:25], v[168:171], v[202:205], v[22:25]
	v_mfma_f32_16x16x32_bf16 v[18:21], v[176:179], v[202:205], v[18:21]
	v_mfma_f32_16x16x32_bf16 v[6:9], v[168:171], v[212:215], v[6:9]
	v_mfma_f32_16x16x32_bf16 v[2:5], v[176:179], v[212:215], v[2:5]
	s_add_i32 s19, s19, 2
	s_add_u32 s14, s14, 0x100
	s_addc_u32 s18, s18, 0
	s_add_u32 s0, s0, 0x100
	s_addc_u32 s1, s1, 0
	s_add_u32 s41, s0, 0xfff80080
	s_addc_u32 s42, s1, -1
	s_add_i32 s51, 0, 0x10000
	s_cmp_eq_u32 s19, 28
	s_cselect_b32 s59, s2, s42
	s_cselect_b32 s58, s3, s41
	v_add_u32_e32 v154, s51, v157
	s_cselect_b32 s43, s8, s18
	s_cselect_b32 s42, s12, s14
	s_cmp_gt_u32 s19, 29
	v_mfma_f32_16x16x32_bf16 v[54:57], v[172:175], v[190:193], v[54:57]
	v_mfma_f32_16x16x32_bf16 v[50:53], v[180:183], v[190:193], v[50:53]
	v_mfma_f32_16x16x32_bf16 v[38:41], v[172:175], v[198:201], v[38:41]
	v_mfma_f32_16x16x32_bf16 v[34:37], v[180:183], v[198:201], v[34:37]
	v_mfma_f32_16x16x32_bf16 v[22:25], v[172:175], v[208:211], v[22:25]
	v_mfma_f32_16x16x32_bf16 v[18:21], v[180:183], v[208:211], v[18:21]
	v_mfma_f32_16x16x32_bf16 v[6:9], v[172:175], v[216:219], v[6:9]
	v_mfma_f32_16x16x32_bf16 v[2:5], v[180:183], v[216:219], v[2:5]
	s_setprio 0
	s_barrier
	s_cbranch_scc0 .Lmy_rot1
	s_and_b64 vcc, exec, s[48:49]
	s_cbranch_vccz .LBB0_1275
	s_barrier
